# heavy diff loop: DMAs moved behind first MFMAs, K-frag reads hoisted, row-sum adds interleaved into exp gaps
# baseline (speedup 1.0000x reference)
.LBB0_301:
	s_add_i32 s81, s70, s74
	s_add_i32 s82, s81, -2
	s_add_i32 s4, s81, -4
	s_cmp_lt_i32 s4, s68
	s_cselect_b32 s4, s4, s82
	s_add_i32 s5, s81, -3
	s_add_i32 s8, s81, -1
	s_cmp_lt_i32 s5, s68
	s_cselect_b32 s80, s5, s8
	s_lshl_b32 s100, s4, 14
	ds_read_b128 v[200:203], v171
	ds_read_b128 v[204:207], v171 offset:4096
	ds_read_b128 v[208:211], v174
	ds_read_b128 v[212:215], v174 offset:4096
	s_lshl_b32 s5, s4, 6
	s_cmp_lt_i32 s4, s68
	v_subrev_u32_e32 v96, s5, v159
	v_sub_u32_e32 v97, 0, v96
	s_cselect_b64 s[4:5], -1, 0
	v_cndmask_b32_e64 v96, v97, v96, s[4:5]
	v_cvt_f32_i32_e32 v96, v96
	v_cndmask_b32_e64 v99, v187, v186, s[4:5]
	v_cndmask_b32_e32 v128, 0, v99, vcc
	v_mul_f32_e64 v97, -v160, v96
	v_cvt_pk_bf16_f32 v97, v97, 0
	v_lshlrev_b32_e32 v97, 16, v97
	v_fma_f32 v96, -v160, v96, -v97
	v_cvt_pk_bf16_f32 v98, v96, 0
	v_lshlrev_b32_e32 v98, 16, v98
	v_sub_f32_e32 v96, v96, v98
	v_cvt_pk_bf16_f32 v97, v97, v98
	v_cvt_pk_bf16_f32 v96, v96, 0
	v_cndmask_b32_e32 v129, 0, v97, vcc
	v_cndmask_b32_e32 v130, 0, v96, vcc
	v_exp_f32_e32 v80, v80
	v_exp_f32_e32 v81, v81
	v_add_f32_e32 v192, 0, v80
	v_add_f32_e32 v192, v81, v192
	v_mfma_f32_32x32x16_bf16 v[112:127], v[152:155], v[128:131], 0
	v_lshl_add_u32 v240, s80, 13, v185
	s_mov_b32 m0, s76
	s_nop 0
	global_load_lds_dwordx4 v240, s[22:23]
	v_mfma_f32_32x32x16_bf16 v[96:111], v[148:151], v[128:131], 0
	s_mov_b32 m0, s77
	v_exp_f32_e32 v82, v82
	v_exp_f32_e32 v83, v83
	global_load_lds_dwordx4 v240, s[24:25]
	v_add_f32_e32 v192, v82, v192
	v_add_f32_e32 v192, v83, v192
	s_waitcnt lgkmcnt(3)
	v_mfma_f32_32x32x16_bf16 v[112:127], v[200:203], v[144:147], v[112:127]
	ds_read_b128 v[216:219], v172
	ds_read_b128 v[220:223], v172 offset:4096
	ds_read_b128 v[224:227], v173
	ds_read_b128 v[228:231], v173 offset:4096
	v_add_u32_e32 v240, s100, v170
	s_mov_b32 m0, s71
	v_exp_f32_e32 v84, v84
	v_exp_f32_e32 v85, v85
	global_load_lds_dwordx4 v240, s[6:7]
	v_add_f32_e32 v192, v84, v192
	v_add_f32_e32 v192, v85, v192
	s_waitcnt lgkmcnt(6)
	v_mfma_f32_32x32x16_bf16 v[96:111], v[204:207], v[144:147], v[96:111]
	v_add_u32_e32 v240, s100, v169
	s_mov_b32 m0, s72
	v_exp_f32_e32 v86, v86
	v_exp_f32_e32 v87, v87
	global_load_lds_dwordx4 v240, s[6:7]
	v_cvt_pk_bf16_f32 v200, v80, v81
	v_cvt_pk_bf16_f32 v201, v82, v83
	v_cvt_pk_bf16_f32 v202, v84, v85
	v_cvt_pk_bf16_f32 v203, v86, v87
	v_add_f32_e32 v192, v86, v192
	v_add_f32_e32 v192, v87, v192
	s_waitcnt lgkmcnt(5)
	v_mfma_f32_32x32x16_bf16 v[112:127], v[208:211], v[140:143], v[112:127]
	v_exp_f32_e32 v88, v88
	v_exp_f32_e32 v89, v89
	v_add_f32_e32 v192, v88, v192
	v_add_f32_e32 v192, v89, v192
	s_waitcnt lgkmcnt(4)
	v_mfma_f32_32x32x16_bf16 v[96:111], v[212:215], v[140:143], v[96:111]
	v_exp_f32_e32 v90, v90
	v_exp_f32_e32 v91, v91
	v_add_f32_e32 v192, v90, v192
	v_add_f32_e32 v192, v91, v192
	ds_read_b64_tr_b16 v[204:205], v175 offset:49152
	ds_read_b64_tr_b16 v[206:207], v176 offset:49152
	ds_read_b64_tr_b16 v[208:209], v177 offset:49152
	ds_read_b64_tr_b16 v[210:211], v178 offset:49152
	ds_read_b64_tr_b16 v[212:213], v179 offset:49152
	ds_read_b64_tr_b16 v[214:215], v182 offset:49152
	ds_read_b64_tr_b16 v[232:233], v183 offset:49152
	ds_read_b64_tr_b16 v[234:235], v184 offset:49152
	s_waitcnt lgkmcnt(11)
	v_mfma_f32_32x32x16_bf16 v[112:127], v[216:219], v[136:139], v[112:127]
	v_exp_f32_e32 v92, v92
	v_exp_f32_e32 v93, v93
	v_add_f32_e32 v192, v92, v192
	v_add_f32_e32 v192, v93, v192
	s_waitcnt lgkmcnt(10)
	v_mfma_f32_32x32x16_bf16 v[96:111], v[220:223], v[136:139], v[96:111]
	v_exp_f32_e32 v94, v94
	v_exp_f32_e32 v95, v95
	v_cvt_pk_bf16_f32 v216, v88, v89
	v_cvt_pk_bf16_f32 v217, v90, v91
	v_cvt_pk_bf16_f32 v218, v92, v93
	v_cvt_pk_bf16_f32 v219, v94, v95
	s_waitcnt lgkmcnt(9)
	v_mfma_f32_32x32x16_bf16 v[112:127], v[224:227], v[132:135], v[112:127]
	v_add_f32_e32 v192, v94, v192
	v_add_f32_e32 v192, v95, v192
	s_waitcnt lgkmcnt(8)
	v_mfma_f32_32x32x16_bf16 v[96:111], v[228:231], v[132:135], v[96:111]
	ds_read_b64_tr_b16 v[220:221], v175 offset:53248
	ds_read_b64_tr_b16 v[222:223], v176 offset:53248
	ds_read_b64_tr_b16 v[224:225], v177 offset:53248
	ds_read_b64_tr_b16 v[226:227], v178 offset:53248
	ds_read_b64_tr_b16 v[228:229], v179 offset:53248
	ds_read_b64_tr_b16 v[230:231], v182 offset:53248
	ds_read_b64_tr_b16 v[236:237], v183 offset:53248
	ds_read_b64_tr_b16 v[238:239], v184 offset:53248
	s_waitcnt lgkmcnt(14)
	v_mfma_f32_32x32x16_bf16 v[48:63], v[204:207], v[200:203], v[48:63]
	v_exp_f32_e32 v64, v64
	v_exp_f32_e32 v65, v65
	v_add_f32_e32 v192, v64, v192
	v_add_f32_e32 v192, v65, v192
	s_waitcnt lgkmcnt(12)
	v_mfma_f32_32x32x16_bf16 v[32:47], v[208:211], v[200:203], v[32:47]
	v_exp_f32_e32 v66, v66
	v_exp_f32_e32 v67, v67
	v_add_f32_e32 v192, v66, v192
	v_add_f32_e32 v192, v67, v192
	s_waitcnt lgkmcnt(10)
	v_mfma_f32_32x32x16_bf16 v[16:31], v[212:215], v[200:203], v[16:31]
	v_exp_f32_e32 v68, v68
	v_exp_f32_e32 v69, v69
	v_add_f32_e32 v192, v68, v192
	v_add_f32_e32 v192, v69, v192
	s_waitcnt lgkmcnt(8)
	v_mfma_f32_32x32x16_bf16 v[0:15], v[232:235], v[200:203], v[0:15]
	v_exp_f32_e32 v70, v70
	v_exp_f32_e32 v71, v71
	v_cvt_pk_bf16_f32 v204, v64, v65
	v_cvt_pk_bf16_f32 v205, v66, v67
	v_cvt_pk_bf16_f32 v206, v68, v69
	v_cvt_pk_bf16_f32 v207, v70, v71
	ds_read_b64_tr_b16 v[200:201], v175 offset:57344
	ds_read_b64_tr_b16 v[202:203], v176 offset:57344
	ds_read_b64_tr_b16 v[208:209], v177 offset:57344
	ds_read_b64_tr_b16 v[210:211], v178 offset:57344
	ds_read_b64_tr_b16 v[212:213], v179 offset:57344
	ds_read_b64_tr_b16 v[214:215], v182 offset:57344
	ds_read_b64_tr_b16 v[232:233], v183 offset:57344
	ds_read_b64_tr_b16 v[234:235], v184 offset:57344
	s_waitcnt lgkmcnt(14)
	v_mfma_f32_32x32x16_bf16 v[48:63], v[220:223], v[216:219], v[48:63]
	v_exp_f32_e32 v72, v72
	v_add_f32_e32 v192, v70, v192
	v_add_f32_e32 v192, v71, v192
	s_waitcnt lgkmcnt(12)
	v_mfma_f32_32x32x16_bf16 v[32:47], v[224:227], v[216:219], v[32:47]
	v_exp_f32_e32 v73, v73
	v_add_f32_e32 v192, v72, v192
	s_waitcnt lgkmcnt(10)
	v_mfma_f32_32x32x16_bf16 v[16:31], v[228:231], v[216:219], v[16:31]
	v_exp_f32_e32 v74, v74
	v_add_f32_e32 v192, v73, v192
	s_waitcnt lgkmcnt(8)
	v_mfma_f32_32x32x16_bf16 v[0:15], v[236:239], v[216:219], v[0:15]
	v_exp_f32_e32 v75, v75
	v_add_f32_e32 v192, v74, v192
	ds_read_b64_tr_b16 v[216:217], v175 offset:61440
	ds_read_b64_tr_b16 v[218:219], v176 offset:61440
	ds_read_b64_tr_b16 v[220:221], v177 offset:61440
	ds_read_b64_tr_b16 v[222:223], v178 offset:61440
	ds_read_b64_tr_b16 v[224:225], v179 offset:61440
	ds_read_b64_tr_b16 v[226:227], v182 offset:61440
	ds_read_b64_tr_b16 v[228:229], v183 offset:61440
	ds_read_b64_tr_b16 v[230:231], v184 offset:61440
	s_waitcnt lgkmcnt(14)
	v_mfma_f32_32x32x16_bf16 v[48:63], v[200:203], v[204:207], v[48:63]
	v_exp_f32_e32 v76, v76
	v_add_f32_e32 v192, v75, v192
	s_waitcnt lgkmcnt(12)
	v_mfma_f32_32x32x16_bf16 v[32:47], v[208:211], v[204:207], v[32:47]
	v_exp_f32_e32 v77, v77
	v_add_f32_e32 v192, v76, v192
	s_waitcnt lgkmcnt(10)
	v_mfma_f32_32x32x16_bf16 v[16:31], v[212:215], v[204:207], v[16:31]
	v_exp_f32_e32 v78, v78
	v_add_f32_e32 v192, v77, v192
	s_waitcnt lgkmcnt(8)
	v_mfma_f32_32x32x16_bf16 v[0:15], v[232:235], v[204:207], v[0:15]
	v_exp_f32_e32 v79, v79
	v_cvt_pk_bf16_f32 v200, v72, v73
	v_cvt_pk_bf16_f32 v201, v74, v75
	v_cvt_pk_bf16_f32 v202, v76, v77
	v_cvt_pk_bf16_f32 v203, v78, v79
	s_waitcnt lgkmcnt(6)
	s_nop 0
	v_mfma_f32_32x32x16_bf16 v[48:63], v[216:219], v[200:203], v[48:63]
	v_add_f32_e32 v192, v78, v192
	v_add_f32_e32 v192, v79, v192
	s_waitcnt lgkmcnt(4)
	v_mfma_f32_32x32x16_bf16 v[32:47], v[220:223], v[200:203], v[32:47]
	v_add_f32_e32 v192, v188, v192
	s_waitcnt lgkmcnt(2)
	v_mfma_f32_32x32x16_bf16 v[16:31], v[224:227], v[200:203], v[16:31]
	s_waitcnt lgkmcnt(0)
	v_mfma_f32_32x32x16_bf16 v[0:15], v[228:231], v[200:203], v[0:15]
	s_waitcnt vmcnt(0) lgkmcnt(0)
	s_barrier
	s_cmp_ge_i32 s74, s20
	s_cbranch_scc1 .LBB0_303
	s_cmp_lt_i32 s82, s68
	s_cselect_b32 s4, s82, s81
	v_lshl_add_u32 v128, s4, 13, v185
	s_mov_b32 s4, m0
	s_mov_b32 m0, s73
	s_nop 0
	global_load_lds_dwordx4 v128, s[22:23]
	s_mov_b32 m0, s4
	s_nop 0
	s_mov_b32 s4, m0
	s_mov_b32 m0, s75
	s_nop 0
	global_load_lds_dwordx4 v128, s[24:25]
	s_mov_b32 m0, s4
.LBB0_303:
	s_lshl_b32 s100, s80, 14
	ds_read_b128 v[188:191], v171 offset:32768
	ds_read_b128 v[200:203], v171 offset:36864
	ds_read_b128 v[204:207], v174 offset:32768
	ds_read_b128 v[208:211], v174 offset:36864
	s_lshl_b32 s4, s80, 6
	s_cmp_lt_i32 s80, s68
	v_subrev_u32_e32 v64, s4, v159
	v_sub_u32_e32 v65, 0, v64
	s_cselect_b64 s[4:5], -1, 0
	v_cndmask_b32_e64 v64, v65, v64, s[4:5]
	v_cvt_f32_i32_e32 v64, v64
	v_cndmask_b32_e64 v67, v187, v186, s[4:5]
	v_cndmask_b32_e32 v128, 0, v67, vcc
	v_mul_f32_e64 v65, -v160, v64
	v_cvt_pk_bf16_f32 v65, v65, 0
	v_lshlrev_b32_e32 v65, 16, v65
	v_fma_f32 v64, -v160, v64, -v65
	v_cvt_pk_bf16_f32 v66, v64, 0
	v_lshlrev_b32_e32 v66, 16, v66
	v_sub_f32_e32 v64, v64, v66
	v_cvt_pk_bf16_f32 v65, v65, v66
	v_cvt_pk_bf16_f32 v64, v64, 0
	v_cndmask_b32_e32 v129, 0, v65, vcc
	v_cndmask_b32_e32 v130, 0, v64, vcc
	v_exp_f32_e32 v224, v112
	v_exp_f32_e32 v225, v113
	v_mfma_f32_32x32x16_bf16 v[80:95], v[152:155], v[128:131], 0
	v_add_f32_e32 v64, 0, v224
	v_add_f32_e32 v64, v225, v64
	v_add_u32_e32 v240, s100, v170
	s_mov_b32 m0, s78
	v_exp_f32_e32 v226, v114
	v_exp_f32_e32 v227, v115
	global_load_lds_dwordx4 v240, s[6:7]
	v_add_f32_e32 v64, v226, v64
	v_add_f32_e32 v228, v227, v64
	v_mfma_f32_32x32x16_bf16 v[64:79], v[148:151], v[128:131], 0
	v_add_u32_e32 v240, s100, v169
	s_mov_b32 m0, s79
	s_waitcnt lgkmcnt(3)
	v_mfma_f32_32x32x16_bf16 v[80:95], v[188:191], v[144:147], v[80:95]
	global_load_lds_dwordx4 v240, s[6:7]
	ds_read_b128 v[112:115], v172 offset:32768
	ds_read_b128 v[212:215], v172 offset:36864
	ds_read_b128 v[216:219], v173 offset:32768
	ds_read_b128 v[220:223], v173 offset:36864
	v_exp_f32_e32 v128, v116
	v_exp_f32_e32 v129, v117
	v_add_f32_e32 v116, v128, v228
	v_add_f32_e32 v130, v129, v116
	s_waitcnt lgkmcnt(6)
	v_mfma_f32_32x32x16_bf16 v[64:79], v[200:203], v[144:147], v[64:79]
	v_exp_f32_e32 v188, v118
	v_exp_f32_e32 v119, v119
	v_cvt_pk_bf16_f32 v116, v224, v225
	v_cvt_pk_bf16_f32 v117, v226, v227
	v_add_f32_e32 v118, v188, v130
	v_add_f32_e32 v130, v119, v118
	v_cvt_pk_bf16_f32 v118, v128, v129
	v_cvt_pk_bf16_f32 v119, v188, v119
	s_waitcnt lgkmcnt(5)
	v_mfma_f32_32x32x16_bf16 v[80:95], v[204:207], v[140:143], v[80:95]
	v_exp_f32_e32 v128, v120
	v_exp_f32_e32 v129, v121
	v_add_f32_e32 v120, v128, v130
	v_add_f32_e32 v120, v129, v120
	s_waitcnt lgkmcnt(4)
	v_mfma_f32_32x32x16_bf16 v[64:79], v[208:211], v[140:143], v[64:79]
	v_exp_f32_e32 v130, v122
	v_exp_f32_e32 v224, v123
	v_add_f32_e32 v120, v130, v120
	v_add_f32_e32 v225, v224, v120
	ds_read_b64_tr_b16 v[120:121], v175 offset:16384
	ds_read_b64_tr_b16 v[122:123], v176 offset:16384
	ds_read_b64_tr_b16 v[188:189], v177 offset:16384
	ds_read_b64_tr_b16 v[190:191], v178 offset:16384
	ds_read_b64_tr_b16 v[200:201], v179 offset:16384
	ds_read_b64_tr_b16 v[202:203], v182 offset:16384
	ds_read_b64_tr_b16 v[204:205], v183 offset:16384
	ds_read_b64_tr_b16 v[206:207], v184 offset:16384
	s_waitcnt lgkmcnt(11)
	v_mfma_f32_32x32x16_bf16 v[80:95], v[112:115], v[136:139], v[80:95]
	v_exp_f32_e32 v124, v124
	v_exp_f32_e32 v125, v125
	v_add_f32_e32 v112, v124, v225
	v_add_f32_e32 v114, v125, v112
	s_waitcnt lgkmcnt(10)
	v_mfma_f32_32x32x16_bf16 v[64:79], v[212:215], v[136:139], v[64:79]
	v_exp_f32_e32 v115, v126
	v_exp_f32_e32 v126, v127
	v_cvt_pk_bf16_f32 v112, v128, v129
	v_cvt_pk_bf16_f32 v113, v130, v224
	v_add_f32_e32 v114, v115, v114
	v_add_f32_e32 v128, v126, v114
	v_cvt_pk_bf16_f32 v114, v124, v125
	v_cvt_pk_bf16_f32 v115, v115, v126
	s_waitcnt lgkmcnt(9)
	v_mfma_f32_32x32x16_bf16 v[80:95], v[216:219], v[132:135], v[80:95]
	s_waitcnt lgkmcnt(8)
	v_mfma_f32_32x32x16_bf16 v[64:79], v[220:223], v[132:135], v[64:79]
	ds_read_b64_tr_b16 v[124:125], v175 offset:20480
	ds_read_b64_tr_b16 v[126:127], v176 offset:20480
	ds_read_b64_tr_b16 v[208:209], v177 offset:20480
	ds_read_b64_tr_b16 v[210:211], v178 offset:20480
	ds_read_b64_tr_b16 v[212:213], v179 offset:20480
	ds_read_b64_tr_b16 v[214:215], v182 offset:20480
	ds_read_b64_tr_b16 v[216:217], v183 offset:20480
	ds_read_b64_tr_b16 v[218:219], v184 offset:20480
	s_waitcnt lgkmcnt(14)
	v_mfma_f32_32x32x16_bf16 v[48:63], v[120:123], v[116:119], v[48:63]
	v_exp_f32_e32 v96, v96
	v_exp_f32_e32 v97, v97
	v_add_f32_e32 v120, v96, v128
	v_add_f32_e32 v120, v97, v120
	s_waitcnt lgkmcnt(12)
	v_mfma_f32_32x32x16_bf16 v[32:47], v[188:191], v[116:119], v[32:47]
	v_exp_f32_e32 v98, v98
	v_exp_f32_e32 v99, v99
	v_add_f32_e32 v120, v98, v120
	v_add_f32_e32 v120, v99, v120
	s_waitcnt lgkmcnt(10)
	v_mfma_f32_32x32x16_bf16 v[16:31], v[200:203], v[116:119], v[16:31]
	v_exp_f32_e32 v100, v100
	v_exp_f32_e32 v101, v101
	v_add_f32_e32 v120, v100, v120
	v_add_f32_e32 v120, v101, v120
	s_waitcnt lgkmcnt(8)
	v_mfma_f32_32x32x16_bf16 v[0:15], v[204:207], v[116:119], v[0:15]
	v_exp_f32_e32 v102, v102
	v_exp_f32_e32 v103, v103
	v_cvt_pk_bf16_f32 v96, v96, v97
	v_cvt_pk_bf16_f32 v97, v98, v99
	v_add_f32_e32 v98, v102, v120
	v_add_f32_e32 v128, v103, v98
	v_cvt_pk_bf16_f32 v98, v100, v101
	v_cvt_pk_bf16_f32 v99, v102, v103
	ds_read_b64_tr_b16 v[100:101], v175 offset:24576
	ds_read_b64_tr_b16 v[102:103], v176 offset:24576
	ds_read_b64_tr_b16 v[116:117], v177 offset:24576
	ds_read_b64_tr_b16 v[118:119], v178 offset:24576
	ds_read_b64_tr_b16 v[120:121], v179 offset:24576
	ds_read_b64_tr_b16 v[122:123], v182 offset:24576
	ds_read_b64_tr_b16 v[188:189], v183 offset:24576
	ds_read_b64_tr_b16 v[190:191], v184 offset:24576
	s_waitcnt lgkmcnt(14)
	v_mfma_f32_32x32x16_bf16 v[48:63], v[124:127], v[112:115], v[48:63]
	v_exp_f32_e32 v129, v104
	s_nop 0
	v_add_f32_e32 v104, v129, v128
	s_waitcnt lgkmcnt(12)
	v_mfma_f32_32x32x16_bf16 v[32:47], v[208:211], v[112:115], v[32:47]
	v_exp_f32_e32 v128, v105
	s_nop 0
	v_add_f32_e32 v104, v128, v104
	s_waitcnt lgkmcnt(10)
	v_mfma_f32_32x32x16_bf16 v[16:31], v[212:215], v[112:115], v[16:31]
	v_exp_f32_e32 v130, v106
	s_nop 0
	v_add_f32_e32 v104, v130, v104
	s_waitcnt lgkmcnt(8)
	v_mfma_f32_32x32x16_bf16 v[0:15], v[216:219], v[112:115], v[0:15]
	v_exp_f32_e32 v204, v107
	s_nop 0
	v_add_f32_e32 v205, v204, v104
	ds_read_b64_tr_b16 v[104:105], v175 offset:28672
	ds_read_b64_tr_b16 v[106:107], v176 offset:28672
	ds_read_b64_tr_b16 v[112:113], v177 offset:28672
	ds_read_b64_tr_b16 v[114:115], v178 offset:28672
	ds_read_b64_tr_b16 v[124:125], v179 offset:28672
	ds_read_b64_tr_b16 v[126:127], v182 offset:28672
	ds_read_b64_tr_b16 v[200:201], v183 offset:28672
	ds_read_b64_tr_b16 v[202:203], v184 offset:28672
	s_waitcnt lgkmcnt(14)
	v_mfma_f32_32x32x16_bf16 v[48:63], v[100:103], v[96:99], v[48:63]
	v_exp_f32_e32 v108, v108
	s_nop 0
	v_add_f32_e32 v100, v108, v205
	s_waitcnt lgkmcnt(12)
	v_mfma_f32_32x32x16_bf16 v[32:47], v[116:119], v[96:99], v[32:47]
	v_exp_f32_e32 v102, v109
	s_nop 0
	v_add_f32_e32 v100, v102, v100
	s_waitcnt lgkmcnt(10)
	v_mfma_f32_32x32x16_bf16 v[16:31], v[120:123], v[96:99], v[16:31]
	v_exp_f32_e32 v103, v110
	s_nop 0
	v_add_f32_e32 v109, v103, v100
	s_waitcnt lgkmcnt(8)
	v_mfma_f32_32x32x16_bf16 v[0:15], v[188:191], v[96:99], v[0:15]
	v_exp_f32_e32 v110, v111
	v_cvt_pk_bf16_f32 v100, v129, v128
	v_cvt_pk_bf16_f32 v101, v130, v204
	v_cvt_pk_bf16_f32 v102, v108, v102
	v_add_f32_e32 v108, v110, v109
	v_cvt_pk_bf16_f32 v103, v103, v110
	s_waitcnt lgkmcnt(6)
	s_nop 0
	v_mfma_f32_32x32x16_bf16 v[48:63], v[104:107], v[100:103], v[48:63]
	s_waitcnt lgkmcnt(4)
	v_mfma_f32_32x32x16_bf16 v[32:47], v[112:115], v[100:103], v[32:47]
	s_waitcnt lgkmcnt(2)
	v_mfma_f32_32x32x16_bf16 v[16:31], v[124:127], v[100:103], v[16:31]
	s_waitcnt lgkmcnt(0)
	v_mfma_f32_32x32x16_bf16 v[0:15], v[200:203], v[100:103], v[0:15]
	s_waitcnt vmcnt(0) lgkmcnt(0)
	s_barrier
	s_add_i32 s4, s74, 2
	s_add_i32 s5, s74, 1
	v_add_f32_e32 v188, v192, v108
	s_cmp_lt_i32 s5, s20
	s_cbranch_scc0 .LBB0_305
	s_mov_b32 s74, s4
	s_branch .LBB0_301

	.amdhsa_kernel _Z9hymba_fwd4Args
		.amdhsa_group_segment_fixed_size 0
		.amdhsa_private_segment_fixed_size 0
		.amdhsa_kernarg_size 408
		.amdhsa_user_sgpr_count 2
		.amdhsa_user_sgpr_dispatch_ptr 0
		.amdhsa_user_sgpr_queue_ptr 0
		.amdhsa_user_sgpr_kernarg_segment_ptr 1
		.amdhsa_user_sgpr_dispatch_id 0
		.amdhsa_user_sgpr_kernarg_preload_length 0
		.amdhsa_user_sgpr_kernarg_preload_offset 0
		.amdhsa_user_sgpr_private_segment_size 0
		.amdhsa_uses_dynamic_stack 0
		.amdhsa_enable_private_segment 0
		.amdhsa_system_sgpr_workgroup_id_x 1
		.amdhsa_system_sgpr_workgroup_id_y 0
		.amdhsa_system_sgpr_workgroup_id_z 0
		.amdhsa_system_sgpr_workgroup_info 0
		.amdhsa_system_vgpr_workitem_id 2
		.amdhsa_next_free_vgpr 256
		.amdhsa_next_free_sgpr 102
		.amdhsa_accum_offset 256
		.amdhsa_reserve_vcc 1
		.amdhsa_float_round_mode_32 0
		.amdhsa_float_round_mode_16_64 0
		.amdhsa_float_denorm_mode_32 3
		.amdhsa_float_denorm_mode_16_64 3
		.amdhsa_dx10_clamp 1
		.amdhsa_ieee_mode 1
		.amdhsa_fp16_overflow 0
		.amdhsa_tg_split 0
		.amdhsa_exception_fp_ieee_invalid_op 0
		.amdhsa_exception_fp_denorm_src 0
		.amdhsa_exception_fp_ieee_div_zero 0
		.amdhsa_exception_fp_ieee_overflow 0
		.amdhsa_exception_fp_ieee_underflow 0
		.amdhsa_exception_fp_ieee_inexact 0
		.amdhsa_exception_int_div_zero 0
	.end_amdhsa_kernel

amdhsa.kernels:
  - .agpr_count:     0
    .args:
      - .offset:         0
        .size:           152
        .value_kind:     by_value
      - .offset:         152
        .size:           4
        .value_kind:     hidden_block_count_x
      - .offset:         156
        .size:           4
        .value_kind:     hidden_block_count_y
      - .offset:         160
        .size:           4
        .value_kind:     hidden_block_count_z
      - .offset:         164
        .size:           2
        .value_kind:     hidden_group_size_x
      - .offset:         166
        .size:           2
        .value_kind:     hidden_group_size_y
      - .offset:         168
        .size:           2
        .value_kind:     hidden_group_size_z
      - .offset:         170
        .size:           2
        .value_kind:     hidden_remainder_x
      - .offset:         172
        .size:           2
        .value_kind:     hidden_remainder_y
      - .offset:         174
        .size:           2
        .value_kind:     hidden_remainder_z
      - .offset:         192
        .size:           8
        .value_kind:     hidden_global_offset_x
      - .offset:         200
        .size:           8
        .value_kind:     hidden_global_offset_y
      - .offset:         208
        .size:           8
        .value_kind:     hidden_global_offset_z
      - .offset:         216
        .size:           2
        .value_kind:     hidden_grid_dims
      - .offset:         240
        .size:           8
        .value_kind:     hidden_multigrid_sync_arg
      - .offset:         272
        .size:           4
        .value_kind:     hidden_dynamic_lds_size
    .group_segment_fixed_size: 0
    .kernarg_segment_align: 8
    .kernarg_segment_size: 408
    .language:       OpenCL C
    .language_version:
      - 2
      - 0
    .max_flat_workgroup_size: 512
    .name:           _Z9hymba_fwd4Args
    .private_segment_fixed_size: 0
    .sgpr_count:     108
    .sgpr_spill_count: 4
    .symbol:         _Z9hymba_fwd4Args.kd
    .uniform_work_group_size: 1
    .uses_dynamic_stack: false
    .vgpr_count:     256
    .vgpr_spill_count: 0
    .wavefront_size: 64
